# P0 row loop: the loop-invariant b_f load (and its vmcnt(0) drain) hoisted out of the per-row body
# baseline (speedup 1.0000x reference)
.LBB0_19:
	s_or_b64 exec, exec, s[6:7]
	s_lshl_b32 s4, s87, 3
	s_ashr_i32 s3, s3, 6
	s_add_i32 s18, s3, s4
	s_lshl_b32 s20, s92, 3
	v_and_b32_e32 v45, 63, v44
	s_cmpk_lt_i32 s18, 0x4000
	s_waitcnt lgkmcnt(0)
	s_barrier
	s_cbranch_scc0 .LBB0_28
	s_add_u32 s24, s72, 0x300000
	s_addc_u32 s25, s73, 0
	s_ashr_i32 s19, s18, 31
	s_lshl_b64 s[4:5], s[18:19], 12
	s_add_u32 s4, s52, s4
	s_addc_u32 s5, s53, s5
	v_lshlrev_b32_e32 v34, 4, v45
	global_load_dwordx4 v[30:33], v34, s[4:5]
	global_load_dwordx4 v[26:29], v34, s[4:5] offset:1024
	global_load_dwordx4 v[22:25], v34, s[4:5] offset:2048
	global_load_dwordx4 v[18:21], v34, s[4:5] offset:3072
	v_mbcnt_lo_u32_b32 v1, -1, 0
	v_mbcnt_hi_u32_b32 v2, -1, v1
	v_and_b32_e32 v1, 64, v2
	v_add_u32_e32 v3, 64, v1
	v_xor_b32_e32 v1, 1, v2
	v_cmp_lt_i32_e32 vcc, v1, v3
	v_xor_b32_e32 v4, 2, v2
	s_lshl_b64 s[4:5], s[18:19], 11
	v_cndmask_b32_e32 v1, v2, v1, vcc
	v_cmp_lt_i32_e32 vcc, v4, v3
	s_ashr_i32 s21, s20, 31
	v_mov_b32_e32 v35, 0
	v_cndmask_b32_e32 v4, v2, v4, vcc
	v_lshlrev_b32_e32 v46, 2, v4
	v_xor_b32_e32 v4, 4, v2
	v_cmp_lt_i32_e32 vcc, v4, v3
	v_bfe_u32 v52, v44, 2, 4
	v_lshl_or_b32 v40, v45, 3, s4
	v_cndmask_b32_e32 v4, v2, v4, vcc
	v_lshlrev_b32_e32 v47, 2, v4
	v_xor_b32_e32 v4, 8, v2
	v_cmp_lt_i32_e32 vcc, v4, v3
	v_mov_b32_e32 v41, s5
	s_lshl_b64 s[28:29], s[20:21], 11
	v_cndmask_b32_e32 v4, v2, v4, vcc
	v_lshlrev_b32_e32 v48, 2, v4
	v_xor_b32_e32 v4, 16, v2
	v_cmp_lt_i32_e32 vcc, v4, v3
	s_lshl_b64 s[4:5], s[18:19], 2
	v_lshl_add_u64 v[36:37], s[52:53], 0, v[34:35]
	v_cndmask_b32_e32 v4, v2, v4, vcc
	v_lshlrev_b32_e32 v49, 2, v4
	v_xor_b32_e32 v4, 32, v2
	v_cmp_lt_i32_e32 vcc, v4, v3
	v_add_u32_e32 v51, 0, v34
	v_lshlrev_b32_e32 v34, 2, v52
	v_cndmask_b32_e32 v2, v2, v4, vcc
	v_lshlrev_b32_e32 v50, 2, v2
	v_and_b32_e32 v2, 32, v44
	v_cmp_eq_u32_e64 s[8:9], 0, v2
	v_and_b32_e32 v2, 16, v44
	v_cmp_eq_u32_e64 s[10:11], 0, v2
	v_and_b32_e32 v2, 8, v44
	v_cmp_eq_u32_e64 s[12:13], 0, v2
	v_and_b32_e32 v2, 4, v44
	v_cmp_eq_u32_e64 s[14:15], 0, v2
	v_and_b32_e32 v2, 3, v44
	v_cmp_eq_u32_e64 s[16:17], 0, v2
	s_add_u32 s4, s4, 0x10000
	s_mov_b32 s27, 0
	v_lshlrev_b32_e32 v1, 2, v1
	v_cmp_eq_u32_e64 s[6:7], 0, v45
	v_lshl_add_u64 v[38:39], s[60:61], 0, v[34:35]
	s_addc_u32 s5, s5, 0
	s_mov_b64 s[98:99], exec
	s_mov_b64 exec, s[16:17]
	global_load_dword v237, v[38:39], off
	s_mov_b64 exec, s[98:99]
	s_lshl_b64 s[30:31], s[20:21], 2
	s_movk_i32 s19, 0x7fff
	s_mov_b32 s21, 0xffff0000
	s_mov_b32 s33, 0x3800000
	v_mov_b32_e32 v34, 0x358637bd
	s_mov_b32 s74, 0x800000
	s_mov_b32 s75, 0xbfb8aa3b
	s_mov_b32 s76, 0xb2a5705f
	s_mov_b32 s77, 0x42ce8ed0
	s_mov_b32 s80, 0xc2b17218
	s_mov_b32 s81, 0x7f800000
	s_mov_b32 s82, 0x3f2aaaab
	v_mov_b32_e32 v53, 0x3ecc95a3
	s_mov_b32 s83, 0x3f317218
	s_mov_b32 s85, 0x33800000
	v_mov_b32_e32 v54, 0x7f800000
	v_mov_b32_e32 v42, 0x3f317218
	s_mov_b32 s26, s18
	v_mov_b32_e32 v2, 0
	v_mov_b32_e32 v3, v35
	v_mov_b32_e32 v4, v35
	v_mov_b32_e32 v5, v35
	v_mov_b32_e32 v6, 0
	v_mov_b32_e32 v7, v35
	v_mov_b32_e32 v8, v35
	v_mov_b32_e32 v9, v35
	v_mov_b32_e32 v10, 0
	v_mov_b32_e32 v11, v35
	v_mov_b32_e32 v12, v35
	v_mov_b32_e32 v13, v35
	v_mov_b32_e32 v14, 0
	v_mov_b32_e32 v15, v35
	v_mov_b32_e32 v16, v35
	v_mov_b32_e32 v17, v35
	s_branch .LBB0_22

.LBB0_26:
	s_or_b64 exec, exec, s[60:61]
	v_bfe_u32 v55, v30, 16, 1
	v_add3_u32 v55, v30, v55, s19
	v_bfe_u32 v58, v31, 16, 1
	v_lshrrev_b32_e32 v55, 16, v55
	v_add3_u32 v58, v31, v58, s19
	v_and_or_b32 v58, v58, s21, v55
	v_bfe_u32 v55, v32, 16, 1
	v_add3_u32 v55, v32, v55, s19
	v_bfe_u32 v59, v33, 16, 1
	v_lshrrev_b32_e32 v55, 16, v55
	v_add3_u32 v59, v33, v59, s19
	v_lshl_add_u64 v[56:57], s[72:73], 0, v[40:41]
	v_and_or_b32 v59, v59, s21, v55
	v_bfe_u32 v55, v26, 16, 1
	v_add_co_u32_e32 v60, vcc, s33, v56
	v_add3_u32 v55, v26, v55, s19
	v_bfe_u32 v56, v27, 16, 1
	v_lshrrev_b32_e32 v55, 16, v55
	v_add3_u32 v56, v27, v56, s19
	v_and_or_b32 v56, v56, s21, v55
	v_bfe_u32 v55, v28, 16, 1
	v_addc_co_u32_e32 v61, vcc, 0, v57, vcc
	v_add3_u32 v55, v28, v55, s19
	v_bfe_u32 v57, v29, 16, 1
	v_lshrrev_b32_e32 v55, 16, v55
	v_add3_u32 v57, v29, v57, s19
	v_and_or_b32 v57, v57, s21, v55
	v_bfe_u32 v55, v22, 16, 1
	global_store_dwordx2 v[60:61], v[56:57], off offset:512
	v_add3_u32 v55, v22, v55, s19
	v_bfe_u32 v56, v23, 16, 1
	v_lshrrev_b32_e32 v55, 16, v55
	v_add3_u32 v56, v23, v56, s19
	v_and_or_b32 v56, v56, s21, v55
	v_bfe_u32 v55, v24, 16, 1
	v_add3_u32 v55, v24, v55, s19
	v_bfe_u32 v57, v25, 16, 1
	v_lshrrev_b32_e32 v55, 16, v55
	v_add3_u32 v57, v25, v57, s19
	v_and_or_b32 v57, v57, s21, v55
	v_bfe_u32 v55, v18, 16, 1
	global_store_dwordx2 v[60:61], v[56:57], off offset:1024
	v_add3_u32 v55, v18, v55, s19
	v_bfe_u32 v56, v19, 16, 1
	v_lshrrev_b32_e32 v55, 16, v55
	v_add3_u32 v56, v19, v56, s19
	v_and_or_b32 v62, v56, s21, v55
	v_bfe_u32 v55, v20, 16, 1
	v_add3_u32 v55, v20, v55, s19
	v_bfe_u32 v63, v21, 16, 1
	global_store_dwordx2 v[60:61], v[58:59], off
	v_lshrrev_b32_e32 v55, 16, v55
	ds_read_b128 v[56:59], v51
	v_add3_u32 v63, v21, v63, s19
	v_and_or_b32 v63, v63, s21, v55
	global_store_dwordx2 v[60:61], v[62:63], off offset:1536
	ds_read_b128 v[60:63], v51 offset:1024
	s_waitcnt lgkmcnt(1)
	v_mul_f32_e32 v55, v31, v57
	v_fmac_f32_e32 v55, v30, v56
	v_mul_f32_e32 v56, v33, v59
	v_fmac_f32_e32 v56, v32, v58
	s_waitcnt lgkmcnt(0)
	v_mul_f32_e32 v61, v27, v61
	v_add_f32_e32 v55, v55, v56
	v_fmac_f32_e32 v61, v26, v60
	v_mul_f32_e32 v60, v29, v63
	ds_read_b128 v[56:59], v51 offset:2048
	v_fmac_f32_e32 v60, v28, v62
	v_add_f32_e32 v55, 0, v55
	v_add_f32_e32 v60, v61, v60
	v_add_f32_e32 v55, v55, v60
	ds_read_b128 v[60:63], v51 offset:3072
	s_waitcnt lgkmcnt(1)
	v_mul_f32_e32 v57, v23, v57
	v_fmac_f32_e32 v57, v22, v56
	v_mul_f32_e32 v56, v25, v59
	v_fmac_f32_e32 v56, v24, v58
	v_add_f32_e32 v56, v57, v56
	s_waitcnt lgkmcnt(0)
	v_mul_f32_e32 v64, v19, v61
	v_mul_f32_e32 v65, v21, v63
	v_add_f32_e32 v55, v55, v56
	v_fmac_f32_e32 v64, v18, v60
	v_fmac_f32_e32 v65, v20, v62
	ds_read_b128 v[56:59], v51 offset:5120
	ds_read_b128 v[60:63], v51 offset:4096
	v_add_f32_e32 v64, v64, v65
	v_add_f32_e32 v55, v55, v64
	ds_read_b128 v[64:67], v51 offset:7168
	ds_read_b128 v[68:71], v51 offset:6144
	s_waitcnt lgkmcnt(3)
	v_mul_f32_e32 v57, v27, v57
	s_waitcnt lgkmcnt(2)
	v_mul_f32_e32 v61, v31, v61
	v_fmac_f32_e32 v61, v30, v60
	v_mul_f32_e32 v60, v33, v63
	v_fmac_f32_e32 v57, v26, v56
	v_mul_f32_e32 v56, v29, v59
	v_fmac_f32_e32 v60, v32, v62
	v_fmac_f32_e32 v56, v28, v58
	v_add_f32_e32 v60, v61, v60
	v_add_f32_e32 v56, v57, v56
	s_waitcnt lgkmcnt(0)
	v_mul_f32_e32 v57, v23, v69
	v_mul_f32_e32 v58, v25, v71
	v_add_f32_e32 v60, 0, v60
	v_fmac_f32_e32 v57, v22, v68
	v_fmac_f32_e32 v58, v24, v70
	v_add_f32_e32 v56, v60, v56
	v_add_f32_e32 v57, v57, v58
	v_add_f32_e32 v56, v56, v57
	v_mul_f32_e32 v57, v19, v65
	v_fmac_f32_e32 v57, v18, v64
	ds_read_b128 v[58:61], v51 offset:9216
	ds_read_b128 v[62:65], v51 offset:8192
	v_mul_f32_e32 v67, v21, v67
	v_fmac_f32_e32 v67, v20, v66
	v_add_f32_e32 v57, v57, v67
	v_add_f32_e32 v56, v56, v57
	ds_read_b128 v[66:69], v51 offset:11264
	ds_read_b128 v[70:73], v51 offset:10240
	s_waitcnt lgkmcnt(2)
	v_mul_f32_e32 v57, v31, v63
	v_fmac_f32_e32 v57, v30, v62
	v_mul_f32_e32 v62, v33, v65
	v_mul_f32_e32 v59, v27, v59
	v_fmac_f32_e32 v62, v32, v64
	v_fmac_f32_e32 v59, v26, v58
	v_mul_f32_e32 v58, v29, v61
	v_add_f32_e32 v57, v57, v62
	v_fmac_f32_e32 v58, v28, v60
	v_add_f32_e32 v57, 0, v57
	v_add_f32_e32 v58, v59, v58
	v_add_f32_e32 v57, v57, v58
	s_waitcnt lgkmcnt(0)
	v_mul_f32_e32 v58, v23, v71
	v_mul_f32_e32 v59, v25, v73
	v_fmac_f32_e32 v58, v22, v70
	v_fmac_f32_e32 v59, v24, v72
	v_add_f32_e32 v58, v58, v59
	v_mul_f32_e32 v67, v19, v67
	v_add_f32_e32 v57, v57, v58
	v_fmac_f32_e32 v67, v18, v66
	v_mul_f32_e32 v66, v21, v69
	ds_read_b128 v[58:61], v51 offset:13312
	ds_read_b128 v[62:65], v51 offset:12288
	v_fmac_f32_e32 v66, v20, v68
	v_add_f32_e32 v66, v67, v66
	v_add_f32_e32 v57, v57, v66
	ds_read_b128 v[66:69], v51 offset:15360
	ds_read_b128 v[70:73], v51 offset:14336
	s_waitcnt lgkmcnt(2)
	v_mul_f32_e32 v63, v31, v63
	v_mul_f32_e32 v59, v27, v59
	v_fmac_f32_e32 v63, v30, v62
	v_mul_f32_e32 v62, v33, v65
	v_fmac_f32_e32 v59, v26, v58
	v_mul_f32_e32 v58, v29, v61
	v_fmac_f32_e32 v62, v32, v64
	v_fmac_f32_e32 v58, v28, v60
	v_add_f32_e32 v62, v63, v62
	v_add_f32_e32 v58, v59, v58
	s_waitcnt lgkmcnt(0)
	v_mul_f32_e32 v59, v23, v71
	v_mul_f32_e32 v60, v25, v73
	v_add_f32_e32 v62, 0, v62
	v_fmac_f32_e32 v59, v22, v70
	v_fmac_f32_e32 v60, v24, v72
	v_add_f32_e32 v58, v62, v58
	v_add_f32_e32 v59, v59, v60
	v_add_f32_e32 v58, v58, v59
	v_mul_f32_e32 v59, v19, v67
	v_mul_f32_e32 v64, v21, v69
	ds_read_b128 v[60:63], v51 offset:16384
	v_fmac_f32_e32 v59, v18, v66
	v_fmac_f32_e32 v64, v20, v68
	v_add_f32_e32 v59, v59, v64
	ds_read_b128 v[64:67], v51 offset:17408
	v_add_f32_e32 v58, v58, v59
	s_waitcnt lgkmcnt(1)
	v_mul_f32_e32 v59, v31, v61
	v_fmac_f32_e32 v59, v30, v60
	v_mul_f32_e32 v60, v33, v63
	v_fmac_f32_e32 v60, v32, v62
	s_waitcnt lgkmcnt(0)
	v_mul_f32_e32 v65, v27, v65
	v_add_f32_e32 v59, v59, v60
	v_fmac_f32_e32 v65, v26, v64
	v_mul_f32_e32 v64, v29, v67
	ds_read_b128 v[60:63], v51 offset:18432
	v_fmac_f32_e32 v64, v28, v66
	v_add_f32_e32 v59, 0, v59
	v_add_f32_e32 v64, v65, v64
	v_add_f32_e32 v59, v59, v64
	ds_read_b128 v[64:67], v51 offset:19456
	s_waitcnt lgkmcnt(1)
	v_mul_f32_e32 v61, v23, v61
	v_fmac_f32_e32 v61, v22, v60
	v_mul_f32_e32 v60, v25, v63
	v_fmac_f32_e32 v60, v24, v62
	v_add_f32_e32 v60, v61, v60
	s_waitcnt lgkmcnt(0)
	v_mul_f32_e32 v68, v19, v65
	v_mul_f32_e32 v69, v21, v67
	v_add_f32_e32 v59, v59, v60
	v_fmac_f32_e32 v68, v18, v64
	v_fmac_f32_e32 v69, v20, v66
	ds_read_b128 v[60:63], v51 offset:21504
	ds_read_b128 v[64:67], v51 offset:20480
	v_add_f32_e32 v68, v68, v69
	v_add_f32_e32 v59, v59, v68
	ds_read_b128 v[68:71], v51 offset:23552
	ds_read_b128 v[72:75], v51 offset:22528
	s_waitcnt lgkmcnt(3)
	v_mul_f32_e32 v61, v27, v61
	s_waitcnt lgkmcnt(2)
	v_mul_f32_e32 v65, v31, v65
	v_fmac_f32_e32 v65, v30, v64
	v_mul_f32_e32 v64, v33, v67
	v_fmac_f32_e32 v61, v26, v60
	v_mul_f32_e32 v60, v29, v63
	v_fmac_f32_e32 v64, v32, v66
	v_fmac_f32_e32 v60, v28, v62
	v_add_f32_e32 v64, v65, v64
	v_add_f32_e32 v60, v61, v60
	s_waitcnt lgkmcnt(0)
	v_mul_f32_e32 v61, v23, v73
	v_mul_f32_e32 v62, v25, v75
	v_add_f32_e32 v64, 0, v64
	v_fmac_f32_e32 v61, v22, v72
	v_fmac_f32_e32 v62, v24, v74
	v_add_f32_e32 v60, v64, v60
	v_add_f32_e32 v61, v61, v62
	v_mul_f32_e32 v69, v19, v69
	v_add_f32_e32 v72, v60, v61
	v_fmac_f32_e32 v69, v18, v68
	v_mul_f32_e32 v68, v21, v71
	ds_read_b128 v[60:63], v51 offset:25600
	ds_read_b128 v[64:67], v51 offset:24576
	v_fmac_f32_e32 v68, v20, v70
	v_add_f32_e32 v68, v69, v68
	v_add_f32_e32 v76, v72, v68
	ds_read_b128 v[68:71], v51 offset:27648
	ds_read_b128 v[72:75], v51 offset:26624
	s_waitcnt lgkmcnt(2)
	v_mul_f32_e32 v65, v31, v65
	v_mul_f32_e32 v61, v27, v61
	v_fmac_f32_e32 v65, v30, v64
	v_mul_f32_e32 v64, v33, v67
	v_fmac_f32_e32 v61, v26, v60
	v_mul_f32_e32 v60, v29, v63
	v_fmac_f32_e32 v64, v32, v66
	v_fmac_f32_e32 v60, v28, v62
	v_add_f32_e32 v64, v65, v64
	v_add_f32_e32 v60, v61, v60
	s_waitcnt lgkmcnt(0)
	v_mul_f32_e32 v61, v23, v73
	v_mul_f32_e32 v62, v25, v75
	v_add_f32_e32 v64, 0, v64
	v_fmac_f32_e32 v61, v22, v72
	v_fmac_f32_e32 v62, v24, v74
	v_add_f32_e32 v60, v64, v60
	v_add_f32_e32 v61, v61, v62
	v_mul_f32_e32 v69, v19, v69
	v_add_f32_e32 v72, v60, v61
	v_fmac_f32_e32 v69, v18, v68
	v_mul_f32_e32 v68, v21, v71
	ds_read_b128 v[60:63], v51 offset:29696
	ds_read_b128 v[64:67], v51 offset:28672
	v_fmac_f32_e32 v68, v20, v70
	v_add_f32_e32 v68, v69, v68
	v_add_f32_e32 v77, v72, v68
	ds_read_b128 v[68:71], v51 offset:31744
	ds_read_b128 v[72:75], v51 offset:30720
	s_waitcnt lgkmcnt(2)
	v_mul_f32_e32 v65, v31, v65
	v_mul_f32_e32 v61, v27, v61
	v_fmac_f32_e32 v65, v30, v64
	v_mul_f32_e32 v64, v33, v67
	v_fmac_f32_e32 v61, v26, v60
	v_mul_f32_e32 v60, v29, v63
	v_fmac_f32_e32 v64, v32, v66
	v_fmac_f32_e32 v60, v28, v62
	v_add_f32_e32 v64, v65, v64
	v_add_f32_e32 v60, v61, v60
	s_waitcnt lgkmcnt(0)
	v_mul_f32_e32 v61, v23, v73
	v_mul_f32_e32 v62, v25, v75
	v_add_f32_e32 v64, 0, v64
	v_fmac_f32_e32 v61, v22, v72
	v_fmac_f32_e32 v62, v24, v74
	v_add_f32_e32 v60, v64, v60
	v_add_f32_e32 v61, v61, v62
	v_add_f32_e32 v64, v60, v61
	v_mul_f32_e32 v65, v19, v69
	v_mul_f32_e32 v66, v21, v71
	ds_read_b128 v[60:63], v51 offset:32768
	v_fmac_f32_e32 v65, v18, v68
	v_fmac_f32_e32 v66, v20, v70
	v_add_f32_e32 v65, v65, v66
	v_add_f32_e32 v78, v64, v65
	ds_read_b128 v[64:67], v51 offset:33792
	s_waitcnt lgkmcnt(1)
	v_mul_f32_e32 v61, v31, v61
	v_fmac_f32_e32 v61, v30, v60
	v_mul_f32_e32 v60, v33, v63
	v_fmac_f32_e32 v60, v32, v62
	v_add_f32_e32 v60, v61, v60
	s_waitcnt lgkmcnt(0)
	v_mul_f32_e32 v65, v27, v65
	v_add_f32_e32 v68, 0, v60
	v_fmac_f32_e32 v65, v26, v64
	v_mul_f32_e32 v64, v29, v67
	ds_read_b128 v[60:63], v51 offset:34816
	v_fmac_f32_e32 v64, v28, v66
	v_add_f32_e32 v64, v65, v64
	v_add_f32_e32 v68, v68, v64
	ds_read_b128 v[64:67], v51 offset:35840
	s_waitcnt lgkmcnt(1)
	v_mul_f32_e32 v61, v23, v61
	v_fmac_f32_e32 v61, v22, v60
	v_mul_f32_e32 v60, v25, v63
	v_fmac_f32_e32 v60, v24, v62
	v_add_f32_e32 v60, v61, v60
	s_waitcnt lgkmcnt(0)
	v_mul_f32_e32 v69, v19, v65
	v_mul_f32_e32 v70, v21, v67
	v_add_f32_e32 v68, v68, v60
	v_fmac_f32_e32 v69, v18, v64
	v_fmac_f32_e32 v70, v20, v66
	ds_read_b128 v[60:63], v51 offset:37888
	ds_read_b128 v[64:67], v51 offset:36864
	v_add_f32_e32 v69, v69, v70
	v_add_f32_e32 v79, v68, v69
	ds_read_b128 v[68:71], v51 offset:39936
	ds_read_b128 v[72:75], v51 offset:38912
	s_waitcnt lgkmcnt(3)
	v_mul_f32_e32 v61, v27, v61
	s_waitcnt lgkmcnt(2)
	v_mul_f32_e32 v65, v31, v65
	v_fmac_f32_e32 v65, v30, v64
	v_mul_f32_e32 v64, v33, v67
	v_fmac_f32_e32 v61, v26, v60
	v_mul_f32_e32 v60, v29, v63
	v_fmac_f32_e32 v64, v32, v66
	v_fmac_f32_e32 v60, v28, v62
	v_add_f32_e32 v64, v65, v64
	v_add_f32_e32 v60, v61, v60
	s_waitcnt lgkmcnt(0)
	v_mul_f32_e32 v61, v23, v73
	v_mul_f32_e32 v62, v25, v75
	v_add_f32_e32 v64, 0, v64
	v_fmac_f32_e32 v61, v22, v72
	v_fmac_f32_e32 v62, v24, v74
	v_add_f32_e32 v60, v64, v60
	v_add_f32_e32 v61, v61, v62
	v_mul_f32_e32 v69, v19, v69
	v_add_f32_e32 v72, v60, v61
	v_fmac_f32_e32 v69, v18, v68
	v_mul_f32_e32 v68, v21, v71
	ds_read_b128 v[60:63], v51 offset:41984
	ds_read_b128 v[64:67], v51 offset:40960
	v_fmac_f32_e32 v68, v20, v70
	v_add_f32_e32 v68, v69, v68
	v_add_f32_e32 v80, v72, v68
	ds_read_b128 v[68:71], v51 offset:44032
	ds_read_b128 v[72:75], v51 offset:43008
	s_waitcnt lgkmcnt(2)
	v_mul_f32_e32 v65, v31, v65
	v_mul_f32_e32 v61, v27, v61
	v_fmac_f32_e32 v65, v30, v64
	v_mul_f32_e32 v64, v33, v67
	v_fmac_f32_e32 v61, v26, v60
	v_mul_f32_e32 v60, v29, v63
	v_fmac_f32_e32 v64, v32, v66
	v_fmac_f32_e32 v60, v28, v62
	v_add_f32_e32 v64, v65, v64
	v_add_f32_e32 v60, v61, v60
	s_waitcnt lgkmcnt(0)
	v_mul_f32_e32 v61, v23, v73
	v_mul_f32_e32 v62, v25, v75
	v_add_f32_e32 v64, 0, v64
	v_fmac_f32_e32 v61, v22, v72
	v_fmac_f32_e32 v62, v24, v74
	v_add_f32_e32 v60, v64, v60
	v_add_f32_e32 v61, v61, v62
	v_mul_f32_e32 v69, v19, v69
	v_add_f32_e32 v72, v60, v61
	v_fmac_f32_e32 v69, v18, v68
	v_mul_f32_e32 v68, v21, v71
	ds_read_b128 v[60:63], v51 offset:46080
	ds_read_b128 v[64:67], v51 offset:45056
	v_fmac_f32_e32 v68, v20, v70
	v_add_f32_e32 v68, v69, v68
	v_add_f32_e32 v81, v72, v68
	ds_read_b128 v[68:71], v51 offset:48128
	ds_read_b128 v[72:75], v51 offset:47104
	s_waitcnt lgkmcnt(2)
	v_mul_f32_e32 v65, v31, v65
	v_mul_f32_e32 v61, v27, v61
	v_fmac_f32_e32 v65, v30, v64
	v_mul_f32_e32 v64, v33, v67
	v_fmac_f32_e32 v61, v26, v60
	v_mul_f32_e32 v60, v29, v63
	v_fmac_f32_e32 v64, v32, v66
	v_fmac_f32_e32 v60, v28, v62
	v_add_f32_e32 v64, v65, v64
	v_add_f32_e32 v60, v61, v60
	s_waitcnt lgkmcnt(0)
	v_mul_f32_e32 v61, v23, v73
	v_mul_f32_e32 v62, v25, v75
	v_add_f32_e32 v64, 0, v64
	v_fmac_f32_e32 v61, v22, v72
	v_fmac_f32_e32 v62, v24, v74
	v_add_f32_e32 v60, v64, v60
	v_add_f32_e32 v61, v61, v62
	v_add_f32_e32 v64, v60, v61
	v_mul_f32_e32 v65, v19, v69
	v_mul_f32_e32 v66, v21, v71
	ds_read_b128 v[60:63], v51 offset:49152
	v_fmac_f32_e32 v65, v18, v68
	v_fmac_f32_e32 v66, v20, v70
	v_add_f32_e32 v65, v65, v66
	v_add_f32_e32 v82, v64, v65
	ds_read_b128 v[64:67], v51 offset:50176
	s_waitcnt lgkmcnt(1)
	v_mul_f32_e32 v61, v31, v61
	v_fmac_f32_e32 v61, v30, v60
	v_mul_f32_e32 v60, v33, v63
	v_fmac_f32_e32 v60, v32, v62
	v_add_f32_e32 v60, v61, v60
	s_waitcnt lgkmcnt(0)
	v_mul_f32_e32 v65, v27, v65
	v_add_f32_e32 v68, 0, v60
	v_fmac_f32_e32 v65, v26, v64
	v_mul_f32_e32 v64, v29, v67
	ds_read_b128 v[60:63], v51 offset:51200
	v_fmac_f32_e32 v64, v28, v66
	v_add_f32_e32 v64, v65, v64
	v_add_f32_e32 v68, v68, v64
	ds_read_b128 v[64:67], v51 offset:52224
	s_waitcnt lgkmcnt(1)
	v_mul_f32_e32 v61, v23, v61
	v_fmac_f32_e32 v61, v22, v60
	v_mul_f32_e32 v60, v25, v63
	v_fmac_f32_e32 v60, v24, v62
	v_add_f32_e32 v60, v61, v60
	s_waitcnt lgkmcnt(0)
	v_mul_f32_e32 v69, v19, v65
	v_mul_f32_e32 v70, v21, v67
	v_add_f32_e32 v68, v68, v60
	v_fmac_f32_e32 v69, v18, v64
	v_fmac_f32_e32 v70, v20, v66
	ds_read_b128 v[60:63], v51 offset:54272
	ds_read_b128 v[64:67], v51 offset:53248
	v_add_f32_e32 v69, v69, v70
	v_add_f32_e32 v83, v68, v69
	ds_read_b128 v[68:71], v51 offset:56320
	ds_read_b128 v[72:75], v51 offset:55296
	s_waitcnt lgkmcnt(3)
	v_mul_f32_e32 v61, v27, v61
	s_waitcnt lgkmcnt(2)
	v_mul_f32_e32 v65, v31, v65
	v_fmac_f32_e32 v65, v30, v64
	v_mul_f32_e32 v64, v33, v67
	v_fmac_f32_e32 v61, v26, v60
	v_mul_f32_e32 v60, v29, v63
	v_fmac_f32_e32 v64, v32, v66
	v_fmac_f32_e32 v60, v28, v62
	v_add_f32_e32 v64, v65, v64
	v_add_f32_e32 v60, v61, v60
	s_waitcnt lgkmcnt(0)
	v_mul_f32_e32 v61, v23, v73
	v_mul_f32_e32 v62, v25, v75
	v_add_f32_e32 v64, 0, v64
	v_fmac_f32_e32 v61, v22, v72
	v_fmac_f32_e32 v62, v24, v74
	v_add_f32_e32 v60, v64, v60
	v_add_f32_e32 v61, v61, v62
	v_mul_f32_e32 v69, v19, v69
	v_add_f32_e32 v72, v60, v61
	v_fmac_f32_e32 v69, v18, v68
	v_mul_f32_e32 v68, v21, v71
	ds_read_b128 v[60:63], v51 offset:58368
	ds_read_b128 v[64:67], v51 offset:57344
	v_fmac_f32_e32 v68, v20, v70
	v_add_f32_e32 v68, v69, v68
	v_add_f32_e32 v84, v72, v68
	ds_read_b128 v[68:71], v51 offset:60416
	ds_read_b128 v[72:75], v51 offset:59392
	s_waitcnt lgkmcnt(2)
	v_mul_f32_e32 v65, v31, v65
	v_mul_f32_e32 v61, v27, v61
	v_fmac_f32_e32 v65, v30, v64
	v_mul_f32_e32 v64, v33, v67
	v_fmac_f32_e32 v61, v26, v60
	v_mul_f32_e32 v60, v29, v63
	v_fmac_f32_e32 v64, v32, v66
	v_fmac_f32_e32 v60, v28, v62
	v_add_f32_e32 v64, v65, v64
	v_add_f32_e32 v60, v61, v60
	s_waitcnt lgkmcnt(0)
	v_mul_f32_e32 v61, v23, v73
	v_mul_f32_e32 v62, v25, v75
	v_add_f32_e32 v64, 0, v64
	v_fmac_f32_e32 v61, v22, v72
	v_fmac_f32_e32 v62, v24, v74
	v_mul_f32_e32 v69, v19, v69
	v_add_f32_e32 v60, v64, v60
	v_add_f32_e32 v61, v61, v62
	v_fmac_f32_e32 v69, v18, v68
	v_mul_f32_e32 v68, v21, v71
	v_add_f32_e32 v72, v60, v61
	v_fmac_f32_e32 v68, v20, v70
	ds_read_b128 v[60:63], v51 offset:62464
	ds_read_b128 v[64:67], v51 offset:61440
	v_add_f32_e32 v68, v69, v68
	v_add_f32_e32 v85, v72, v68
	ds_read_b128 v[68:71], v51 offset:64512
	ds_read_b128 v[72:75], v51 offset:63488
	s_waitcnt lgkmcnt(3)
	v_mul_f32_e32 v27, v27, v61
	s_waitcnt lgkmcnt(2)
	v_mul_f32_e32 v31, v31, v65
	v_fmac_f32_e32 v31, v30, v64
	v_mul_f32_e32 v30, v33, v67
	v_fmac_f32_e32 v30, v32, v66
	v_fmac_f32_e32 v27, v26, v60
	v_mul_f32_e32 v26, v29, v63
	s_waitcnt lgkmcnt(0)
	v_mul_f32_e32 v23, v23, v73
	v_add_f32_e32 v30, v31, v30
	v_fmac_f32_e32 v26, v28, v62
	v_fmac_f32_e32 v23, v22, v72
	v_mul_f32_e32 v22, v25, v75
	v_mul_f32_e32 v19, v19, v69
	v_add_f32_e32 v30, 0, v30
	v_add_f32_e32 v26, v27, v26
	v_fmac_f32_e32 v22, v24, v74
	v_fmac_f32_e32 v19, v18, v68
	v_mul_f32_e32 v18, v21, v71
	v_add_f32_e32 v26, v30, v26
	v_add_f32_e32 v22, v23, v22
	v_fmac_f32_e32 v18, v20, v70
	v_cndmask_b32_e64 v20, v55, v79, s[8:9]
	v_add_f32_e32 v22, v26, v22
	v_add_f32_e32 v18, v19, v18
	ds_bpermute_b32 v20, v50, v20
	v_cndmask_b32_e64 v21, v56, v80, s[8:9]
	v_add_f32_e32 v18, v22, v18
	ds_bpermute_b32 v21, v50, v21
	v_cndmask_b32_e64 v22, v57, v81, s[8:9]
	ds_bpermute_b32 v22, v50, v22
	v_cndmask_b32_e64 v23, v58, v82, s[8:9]
	ds_bpermute_b32 v23, v50, v23
	v_cndmask_b32_e64 v24, v59, v83, s[8:9]
	v_cndmask_b32_e64 v19, v79, v55, s[8:9]
	ds_bpermute_b32 v24, v50, v24
	v_cndmask_b32_e64 v25, v76, v84, s[8:9]
	s_waitcnt lgkmcnt(4)
	v_add_f32_e32 v19, v19, v20
	v_cndmask_b32_e64 v20, v80, v56, s[8:9]
	ds_bpermute_b32 v25, v50, v25
	v_cndmask_b32_e64 v26, v77, v85, s[8:9]
	v_cndmask_b32_e64 v27, v78, v18, s[8:9]
	s_waitcnt lgkmcnt(4)
	v_add_f32_e32 v20, v20, v21
	v_cndmask_b32_e64 v21, v81, v57, s[8:9]
	ds_bpermute_b32 v26, v50, v26
	ds_bpermute_b32 v27, v50, v27
	s_waitcnt lgkmcnt(5)
	v_add_f32_e32 v21, v21, v22
	v_cndmask_b32_e64 v22, v82, v58, s[8:9]
	s_waitcnt lgkmcnt(4)
	v_add_f32_e32 v22, v22, v23
	v_cndmask_b32_e64 v23, v83, v59, s[8:9]
	s_waitcnt lgkmcnt(3)
	v_add_f32_e32 v23, v23, v24
	v_cndmask_b32_e64 v24, v84, v76, s[8:9]
	s_waitcnt lgkmcnt(2)
	v_add_f32_e32 v24, v24, v25
	v_cndmask_b32_e64 v25, v85, v77, s[8:9]
	v_cndmask_b32_e64 v18, v18, v78, s[8:9]
	s_waitcnt lgkmcnt(1)
	v_add_f32_e32 v25, v25, v26
	s_waitcnt lgkmcnt(0)
	v_add_f32_e32 v18, v18, v27
	v_cndmask_b32_e64 v28, v19, v23, s[10:11]
	v_cndmask_b32_e64 v19, v23, v19, s[10:11]
	v_cndmask_b32_e64 v23, v24, v20, s[10:11]
	v_cndmask_b32_e64 v20, v20, v24, s[10:11]
	v_cndmask_b32_e64 v24, v21, v25, s[10:11]
	v_cndmask_b32_e64 v26, v22, v18, s[10:11]
	ds_bpermute_b32 v28, v49, v28
	ds_bpermute_b32 v20, v49, v20
	ds_bpermute_b32 v24, v49, v24
	ds_bpermute_b32 v26, v49, v26
	v_cndmask_b32_e64 v21, v25, v21, s[10:11]
	v_cndmask_b32_e64 v18, v18, v22, s[10:11]
	s_waitcnt lgkmcnt(3)
	v_add_f32_e32 v19, v19, v28
	s_waitcnt lgkmcnt(2)
	v_add_f32_e32 v20, v23, v20
	s_waitcnt lgkmcnt(1)
	v_add_f32_e32 v21, v21, v24
	s_waitcnt lgkmcnt(0)
	v_add_f32_e32 v18, v18, v26
	v_cndmask_b32_e64 v22, v19, v21, s[12:13]
	v_cndmask_b32_e64 v23, v20, v18, s[12:13]
	ds_bpermute_b32 v22, v48, v22
	ds_bpermute_b32 v23, v48, v23
	v_cndmask_b32_e64 v19, v21, v19, s[12:13]
	v_cndmask_b32_e64 v18, v18, v20, s[12:13]
	s_waitcnt lgkmcnt(1)
	v_add_f32_e32 v19, v19, v22
	s_waitcnt lgkmcnt(0)
	v_add_f32_e32 v18, v18, v23
	v_cndmask_b32_e64 v20, v19, v18, s[14:15]
	ds_bpermute_b32 v20, v47, v20
	v_cndmask_b32_e64 v18, v18, v19, s[14:15]
	s_waitcnt lgkmcnt(0)
	v_add_f32_e32 v18, v18, v20
	ds_bpermute_b32 v19, v46, v18
	s_waitcnt lgkmcnt(0)
	v_add_f32_e32 v18, v18, v19
	ds_bpermute_b32 v19, v1, v18
	s_and_saveexec_b64 s[60:61], s[16:17]
	s_cbranch_execz .LBB0_21
	v_mov_b32_e32 v20, v237
	v_fmamk_f32 v21, v43, 0x3a800000, v34
	s_waitcnt lgkmcnt(0)
	v_add_f32_e32 v22, v18, v19
	v_mul_f32_e32 v18, 0x4b800000, v21
	v_cmp_gt_f32_e32 vcc, s74, v21
	s_ashr_i32 s35, s26, 9
	s_and_b32 s26, s26, 0x1fff
	v_cndmask_b32_e32 v18, v21, v18, vcc
	v_rsq_f32_e32 v21, v18
	v_and_or_b32 v18, s35, -16, v52
	v_ashrrev_i32_e32 v19, 31, v18
	v_lshlrev_b64 v[18:19], 15, v[18:19]
	v_mul_f32_e32 v23, 0x45800000, v21
	v_cndmask_b32_e32 v21, v21, v23, vcc
	s_lshl_b32 s26, s26, 2
	v_lshl_add_u64 v[18:19], s[24:25], 0, v[18:19]
	v_lshl_add_u64 v[18:19], v[18:19], 0, s[26:27]
	v_fmac_f32_e32 v20, v21, v22
	v_mul_f32_e64 v21, |v20|, s75
	v_fma_f32 v22, |v20|, s75, -v21
	v_rndne_f32_e32 v23, v21
	v_fma_f32 v22, |v20|, s76, v22
	v_sub_f32_e32 v21, v21, v23
	v_add_f32_e32 v21, v21, v22
	v_cvt_i32_f32_e32 v23, v23
	v_exp_f32_e32 v21, v21
	v_cmp_ngt_f32_e64 vcc, |v20|, s77
	v_min_f32_e32 v55, 0, v20
	v_ldexp_f32 v21, v21, v23
	v_cndmask_b32_e32 v21, 0, v21, vcc
	v_cmp_nlt_f32_e64 vcc, |v20|, s80
	s_nop 1
	v_cndmask_b32_e32 v56, v54, v21, vcc
	v_add_f32_e32 v22, 1.0, v56
	v_add_f32_e32 v23, -1.0, v22
	v_frexp_mant_f32_e32 v24, v22
	v_cvt_f64_f32_e32 v[20:21], v22
	v_sub_f32_e32 v25, v23, v22
	v_frexp_exp_i32_f64_e32 v20, v[20:21]
	v_cmp_gt_f32_e32 vcc, s82, v24
	v_sub_f32_e32 v23, v56, v23
	v_add_f32_e32 v21, 1.0, v25
	v_subbrev_co_u32_e32 v20, vcc, 0, v20, vcc
	v_add_f32_e32 v21, v23, v21
	v_sub_u32_e32 v23, 0, v20
	v_ldexp_f32 v22, v22, v23
	v_add_f32_e32 v24, -1.0, v22
	v_add_f32_e32 v25, 1.0, v22
	v_ldexp_f32 v21, v21, v23
	v_add_f32_e32 v23, 1.0, v24
	v_add_f32_e32 v26, -1.0, v25
	v_sub_f32_e32 v23, v22, v23
	v_sub_f32_e32 v22, v22, v26
	v_add_f32_e32 v26, v21, v23
	v_add_f32_e32 v21, v21, v22
	v_add_f32_e32 v28, v25, v21
	v_rcp_f32_e32 v29, v28
	v_add_f32_e32 v23, v24, v26
	v_sub_f32_e32 v24, v24, v23
	v_sub_f32_e32 v22, v25, v28
	v_mul_f32_e32 v31, v23, v29
	v_add_f32_e32 v30, v26, v24
	v_mul_f32_e32 v24, v28, v31
	v_add_f32_e32 v21, v21, v22
	v_fma_f32 v26, v31, v28, -v24
	v_fmac_f32_e32 v26, v31, v21
	v_add_f32_e32 v22, v24, v26
	v_sub_f32_e32 v25, v23, v22
	v_mov_b32_e32 v27, v22
	v_pk_add_f32 v[22:23], v[22:23], v[24:25] neg_lo:[0,1] neg_hi:[0,1]
	v_cvt_f32_i32_e32 v20, v20
	v_pk_add_f32 v[22:23], v[22:23], v[26:27] neg_lo:[0,1] neg_hi:[0,1]
	v_cmp_neq_f32_e32 vcc, s81, v56
	v_add_f32_e32 v23, v30, v23
	v_add_f32_e32 v22, v22, v23
	v_add_f32_e32 v23, v25, v22
	v_mul_f32_e32 v27, v29, v23
	v_mul_f32_e32 v24, v28, v27
	v_sub_f32_e32 v25, v25, v23
	v_add_f32_e32 v32, v31, v27
	v_fma_f32 v26, v27, v28, -v24
	v_add_f32_e32 v30, v22, v25
	v_sub_f32_e32 v22, v32, v31
	v_fmac_f32_e32 v26, v27, v21
	v_sub_f32_e32 v21, v27, v22
	v_add_f32_e32 v22, v24, v26
	v_sub_f32_e32 v25, v23, v22
	v_mov_b32_e32 v27, v22
	v_pk_add_f32 v[22:23], v[22:23], v[24:25] neg_lo:[0,1] neg_hi:[0,1]
	s_nop 0
	v_pk_add_f32 v[22:23], v[22:23], v[26:27] neg_lo:[0,1] neg_hi:[0,1]
	s_nop 0
	v_add_f32_e32 v23, v30, v23
	v_add_f32_e32 v22, v22, v23
	v_add_f32_e32 v22, v25, v22
	v_mul_f32_e32 v22, v29, v22
	v_add_f32_e32 v21, v21, v22
	v_add_f32_e32 v22, v32, v21
	v_mul_f32_e32 v24, v22, v22
	v_sub_f32_e32 v25, v22, v32
	v_fmamk_f32 v26, v24, 0x3e9b6dac, v53
	v_sub_f32_e32 v25, v21, v25
	v_mul_f32_e32 v21, v22, v24
	v_fmaak_f32 v43, v24, v26, 0x3f2aaada
	v_ldexp_f32 v27, v25, 1
	v_pk_mul_f32 v[24:25], v[20:21], v[42:43]
	v_ldexp_f32 v23, v22, 1
	v_fma_f32 v22, v20, s83, -v24
	v_fmac_f32_e32 v22, 0xb102e308, v20
	v_pk_add_f32 v[20:21], v[24:25], v[22:23]
	v_mov_b32_e32 v26, v24
	v_sub_f32_e32 v30, v21, v23
	v_pk_add_f32 v[28:29], v[20:21], v[24:25] neg_lo:[0,1] neg_hi:[0,1]
	v_sub_f32_e32 v24, v25, v30
	v_add_f32_e32 v27, v27, v24
	v_pk_add_f32 v[24:25], v[20:21], v[26:27]
	v_mov_b32_e32 v23, v20
	v_mov_b32_e32 v29, v25
	v_pk_add_f32 v[32:33], v[22:23], v[28:29] neg_lo:[0,1] neg_hi:[0,1]
	v_pk_add_f32 v[22:23], v[22:23], v[28:29]
	v_mov_b32_e32 v31, v20
	v_pk_add_f32 v[28:29], v[22:23], v[20:21] op_sel:[1,0] op_sel_hi:[0,1] neg_lo:[0,1] neg_hi:[0,1]
	v_mov_b32_e32 v30, v27
	v_mov_b32_e32 v26, v25
	v_mov_b32_e32 v27, v23
	v_pk_mov_b32 v[20:21], v[20:21], v[28:29] op_sel:[1,0]
	v_pk_add_f32 v[24:25], v[24:25], v[28:29] op_sel_hi:[1,0] neg_lo:[0,1] neg_hi:[0,1]
	v_pk_add_f32 v[20:21], v[26:27], v[20:21] neg_lo:[0,1] neg_hi:[0,1]
	v_mov_b32_e32 v24, v32
	v_pk_add_f32 v[20:21], v[30:31], v[20:21] neg_lo:[0,1] neg_hi:[0,1]
	v_mov_b32_e32 v33, v23
	v_pk_add_f32 v[24:25], v[24:25], v[20:21]
	s_nop 0
	v_pk_add_f32 v[26:27], v[24:25], v[24:25] op_sel:[0,1] op_sel_hi:[1,0]
	s_nop 0
	v_pk_add_f32 v[22:23], v[22:23], v[26:27] op_sel:[1,0] op_sel_hi:[0,1]
	v_mov_b32_e32 v25, v22
	v_mov_b32_e32 v21, v26
	v_pk_add_f32 v[26:27], v[24:25], v[32:33] neg_lo:[0,1] neg_hi:[0,1]
	s_nop 0
	v_sub_f32_e32 v23, v24, v26
	v_pk_add_f32 v[20:21], v[20:21], v[26:27] neg_lo:[0,1] neg_hi:[0,1]
	v_sub_f32_e32 v23, v32, v23
	v_add_f32_e32 v20, v20, v23
	v_add_f32_e32 v20, v20, v21
	v_add_f32_e32 v20, v22, v20
	v_cndmask_b32_e32 v20, v54, v20, vcc
	v_cmp_lt_f32_e64 vcc, |v56|, s85
	s_nop 1
	v_cndmask_b32_e32 v20, v20, v56, vcc
	v_sub_f32_e32 v20, v55, v20
	global_store_dword v[18:19], v20, off
	s_branch .LBB0_21
